# GQA loop: every-4th-tile window check replaced by a one-compare filter on the tile sum of exp2, exact check redone only if the filter trips
# baseline (speedup 1.0000x reference)
.LBB0_133:
	v_exp_f32_e32 v32, v32
	v_exp_f32_e32 v33, v33
	v_exp_f32_e32 v34, v34
	v_exp_f32_e32 v35, v35
	v_add_f32_e32 v96, 0, v32
	v_exp_f32_e32 v36, v36
	v_add_f32_e32 v96, v33, v96
	v_exp_f32_e32 v37, v37
	v_add_f32_e32 v96, v34, v96
	v_exp_f32_e32 v38, v38
	v_add_f32_e32 v96, v35, v96
	v_exp_f32_e32 v39, v39
	v_add_f32_e32 v96, v36, v96
	v_exp_f32_e32 v40, v40
	v_exp_f32_e32 v48, v48
	v_add_f32_e32 v96, v37, v96
	v_exp_f32_e32 v41, v41
	v_cvt_pk_bf16_f32 v32, v32, v33
	v_cvt_pk_bf16_f32 v33, v34, v35
	v_cvt_pk_bf16_f32 v34, v36, v37
	v_exp_f32_e32 v37, v16
	v_exp_f32_e32 v36, v0
	v_exp_f32_e32 v49, v49
	v_add_f32_e32 v96, v38, v96
	v_exp_f32_e32 v17, v17
	v_exp_f32_e32 v16, v1
	v_exp_f32_e32 v50, v50
	v_add_f32_e32 v96, v39, v96
	v_cvt_pk_bf16_f32 v35, v38, v39
	v_exp_f32_e32 v39, v18
	v_exp_f32_e32 v38, v2
	v_exp_f32_e32 v51, v51
	v_add_f32_e32 v96, v40, v96
	v_exp_f32_e32 v19, v19
	v_exp_f32_e32 v18, v3
	v_add_f32_e32 v97, 0, v48
	v_exp_f32_e32 v52, v52
	v_add_f32_e32 v96, v41, v96
	v_cvt_pk_bf16_f32 v100, v40, v41
	v_pk_add_f32 v[0:1], v[36:37], 0 op_sel_hi:[1,0]
	v_exp_f32_e32 v41, v20
	v_exp_f32_e32 v40, v4
	v_add_f32_e32 v97, v49, v97
	v_exp_f32_e32 v53, v53
	v_pk_add_f32 v[0:1], v[16:17], v[0:1]
	v_exp_f32_e32 v21, v21
	v_exp_f32_e32 v20, v5
	v_add_f32_e32 v97, v50, v97
	v_exp_f32_e32 v54, v54
	v_pk_add_f32 v[0:1], v[38:39], v[0:1]
	v_exp_f32_e32 v5, v22
	v_exp_f32_e32 v4, v6
	v_add_f32_e32 v97, v51, v97
	v_exp_f32_e32 v55, v55
	v_pk_add_f32 v[0:1], v[18:19], v[0:1]
	v_exp_f32_e32 v23, v23
	v_exp_f32_e32 v22, v7
	v_add_f32_e32 v97, v52, v97
	v_exp_f32_e32 v56, v56
	v_exp_f32_e32 v7, v24
	v_exp_f32_e32 v6, v8
	v_pk_add_f32 v[0:1], v[40:41], v[0:1]
	v_add_f32_e32 v97, v53, v97
	v_exp_f32_e32 v57, v57
	v_exp_f32_e32 v25, v25
	v_exp_f32_e32 v24, v9
	v_pk_add_f32 v[0:1], v[20:21], v[0:1]
	v_add_f32_e32 v97, v54, v97
	v_exp_f32_e32 v42, v42
	v_exp_f32_e32 v58, v58
	v_exp_f32_e32 v9, v26
	v_exp_f32_e32 v8, v10
	v_pk_add_f32 v[0:1], v[4:5], v[0:1]
	v_add_f32_e32 v97, v55, v97
	v_exp_f32_e32 v43, v43
	v_exp_f32_e32 v59, v59
	v_exp_f32_e32 v27, v27
	v_exp_f32_e32 v26, v11
	v_pk_add_f32 v[0:1], v[22:23], v[0:1]
	v_add_f32_e32 v97, v56, v97
	v_exp_f32_e32 v44, v44
	v_exp_f32_e32 v60, v60
	v_exp_f32_e32 v11, v28
	v_exp_f32_e32 v10, v12
	v_pk_add_f32 v[0:1], v[6:7], v[0:1]
	v_add_f32_e32 v97, v57, v97
	v_exp_f32_e32 v45, v45
	v_exp_f32_e32 v61, v61
	v_exp_f32_e32 v29, v29
	v_exp_f32_e32 v28, v13
	v_pk_add_f32 v[0:1], v[24:25], v[0:1]
	v_add_f32_e32 v96, v42, v96
	v_add_f32_e32 v97, v58, v97
	v_exp_f32_e32 v46, v46
	v_exp_f32_e32 v62, v62
	v_exp_f32_e32 v13, v30
	v_exp_f32_e32 v12, v14
	v_pk_add_f32 v[0:1], v[8:9], v[0:1]
	v_add_f32_e32 v96, v43, v96
	v_add_f32_e32 v97, v59, v97
	v_exp_f32_e32 v47, v47
	v_exp_f32_e32 v63, v63
	v_exp_f32_e32 v31, v31
	v_exp_f32_e32 v30, v15
	v_pk_add_f32 v[0:1], v[26:27], v[0:1]
	v_add_f32_e32 v96, v44, v96
	v_add_f32_e32 v97, v60, v97
	v_pk_add_f32 v[0:1], v[10:11], v[0:1]
	v_add_f32_e32 v96, v45, v96
	v_add_f32_e32 v97, v61, v97
	v_pk_add_f32 v[0:1], v[28:29], v[0:1]
	v_add_f32_e32 v96, v46, v96
	v_add_f32_e32 v97, v62, v97
	v_pk_add_f32 v[0:1], v[12:13], v[0:1]
	v_add_f32_e32 v96, v47, v96
	v_add_f32_e32 v97, v63, v97
	v_pk_add_f32 v[0:1], v[30:31], v[0:1]
	v_add_f32_e32 v96, v97, v96
	v_add_f32_e32 v0, v0, v1
	v_add_f32_e32 v222, 0, v96
	s_sub_i32 s8, 0x84, s13
	v_add_f32_e32 v227, 0, v0
	v_cvt_pk_bf16_f32 v0, v37, v17
	v_cvt_pk_bf16_f32 v1, v39, v19
	v_cvt_pk_bf16_f32 v2, v41, v21
	v_cvt_pk_bf16_f32 v3, v5, v23
	v_cvt_pk_bf16_f32 v96, v48, v49
	v_cvt_pk_bf16_f32 v97, v50, v51
	v_cvt_pk_bf16_f32 v98, v52, v53
	v_cvt_pk_bf16_f32 v99, v54, v55
	v_cvt_pk_bf16_f32 v101, v42, v43
	v_cvt_pk_bf16_f32 v102, v44, v45
	v_cvt_pk_bf16_f32 v103, v46, v47
	v_cvt_pk_bf16_f32 v104, v56, v57
	v_cvt_pk_bf16_f32 v105, v58, v59
	v_cvt_pk_bf16_f32 v106, v60, v61
	v_cvt_pk_bf16_f32 v107, v62, v63
	v_cvt_pk_bf16_f32 v108, v36, v16
	v_cvt_pk_bf16_f32 v109, v38, v18
	v_cvt_pk_bf16_f32 v110, v40, v20
	v_cvt_pk_bf16_f32 v111, v4, v22
	v_cvt_pk_bf16_f32 v112, v7, v25
	v_cvt_pk_bf16_f32 v113, v9, v27
	v_cvt_pk_bf16_f32 v114, v11, v29
	v_cvt_pk_bf16_f32 v115, v13, v31
	v_cvt_pk_bf16_f32 v116, v6, v24
	v_cvt_pk_bf16_f32 v117, v8, v26
	v_cvt_pk_bf16_f32 v118, v10, v28
	v_cvt_pk_bf16_f32 v119, v12, v30
	s_waitcnt lgkmcnt(0)
	v_mfma_f32_32x32x16_bf16 v[48:63], v[88:91], v[32:35], 0
	s_waitcnt vmcnt(0)
	s_mov_b32 s10, 0
	s_movk_i32 s45, 0x4000
	s_waitcnt vmcnt(0)
	s_barrier
	v_mfma_f32_32x32x16_bf16 v[32:47], v[92:95], v[32:35], 0
	v_mfma_f32_32x32x16_bf16 v[16:31], v[88:91], v[0:3], 0
	v_mfma_f32_32x32x16_bf16 v[0:15], v[92:95], v[0:3], 0
	v_mfma_f32_32x32x16_bf16 v[48:63], v[84:87], v[100:103], v[48:63]
	v_mfma_f32_32x32x16_bf16 v[32:47], v[80:83], v[100:103], v[32:47]
	v_mfma_f32_32x32x16_bf16 v[16:31], v[84:87], v[112:115], v[16:31]
	v_mfma_f32_32x32x16_bf16 v[0:15], v[80:83], v[112:115], v[0:15]
	v_mfma_f32_32x32x16_bf16 v[48:63], v[76:79], v[96:99], v[48:63]
	v_mfma_f32_32x32x16_bf16 v[32:47], v[72:75], v[96:99], v[32:47]
	v_mfma_f32_32x32x16_bf16 v[16:31], v[76:79], v[108:111], v[16:31]
	v_mfma_f32_32x32x16_bf16 v[0:15], v[72:75], v[108:111], v[0:15]
	v_mfma_f32_32x32x16_bf16 v[48:63], v[68:71], v[104:107], v[48:63]
	v_mfma_f32_32x32x16_bf16 v[32:47], v[64:67], v[104:107], v[32:47]
	v_mfma_f32_32x32x16_bf16 v[16:31], v[68:71], v[116:119], v[16:31]
	v_mfma_f32_32x32x16_bf16 v[0:15], v[64:67], v[116:119], v[0:15]
	v_readfirstlane_b32 s98, v213
	v_readfirstlane_b32 s99, v241
	v_lshlrev_b32_e32 v192, 1, v192
	v_lshlrev_b32_e32 v216, 1, v216
	v_lshlrev_b32_e32 v214, 1, v214
	v_lshlrev_b32_e32 v218, 1, v218
	v_add_u32_e32 v243, v242, v243
	v_add_u32_e32 v244, v242, v244
	v_add_u32_e32 v245, v242, v245
	v_add_u32_e32 v246, v242, v246
	v_add_u32_e32 v248, v247, v248
	v_add_u32_e32 v249, v247, v249
	v_add_u32_e32 v250, v247, v250
	v_add_u32_e32 v251, v247, v251
	s_mov_b32 s100, 0x7f800000
	s_branch .LBB0_135
.LBB0_134:
	v_exp_f32_e32 v228, v96
	v_exp_f32_e32 v112, v112
	v_exp_f32_e32 v96, v113
	v_exp_f32_e32 v113, v97
	v_exp_f32_e32 v233, v98
	v_exp_f32_e32 v114, v114
	v_exp_f32_e32 v98, v115
	v_add_f32_e32 v229, v113, v228
	v_exp_f32_e32 v115, v99
	v_exp_f32_e32 v116, v116
	v_add_f32_e32 v97, v96, v112
	v_add_f32_e32 v99, v233, v229
	v_exp_f32_e32 v229, v100
	v_exp_f32_e32 v100, v117
	v_add_f32_e32 v97, v114, v97
	v_exp_f32_e32 v117, v101
	v_exp_f32_e32 v101, v118
	v_add_f32_e32 v97, v98, v97
	v_exp_f32_e32 v118, v102
	v_exp_f32_e32 v102, v119
	v_add_f32_e32 v99, v115, v99
	v_add_f32_e32 v97, v116, v97
	v_exp_f32_e32 v103, v103
	v_exp_f32_e32 v119, v120
	v_add_f32_e32 v99, v229, v99
	v_add_f32_e32 v97, v100, v97
	v_exp_f32_e32 v120, v104
	v_exp_f32_e32 v104, v121
	v_add_f32_e32 v99, v117, v99
	v_add_f32_e32 v97, v101, v97
	v_exp_f32_e32 v121, v105
	v_exp_f32_e32 v105, v122
	v_add_f32_e32 v99, v118, v99
	v_add_f32_e32 v97, v102, v97
	v_exp_f32_e32 v122, v106
	v_exp_f32_e32 v106, v123
	v_add_f32_e32 v99, v103, v99
	v_add_f32_e32 v97, v119, v97
	v_exp_f32_e32 v123, v107
	v_exp_f32_e32 v107, v124
	v_add_f32_e32 v99, v120, v99
	v_add_f32_e32 v97, v104, v97
	v_exp_f32_e32 v124, v108
	v_exp_f32_e32 v108, v125
	v_add_f32_e32 v99, v121, v99
	v_add_f32_e32 v97, v105, v97
	v_exp_f32_e32 v125, v109
	v_exp_f32_e32 v109, v126
	v_exp_f32_e32 v126, v110
	v_exp_f32_e32 v110, v127
	v_add_f32_e32 v99, v122, v99
	v_add_f32_e32 v97, v106, v97
	v_add_f32_e32 v99, v123, v99
	v_add_f32_e32 v97, v107, v97
	v_exp_f32_e32 v111, v111
	v_add_f32_e32 v99, v124, v99
	v_add_f32_e32 v97, v108, v97
	v_cvt_pk_bf16_f32 v105, v105, v106
	v_cvt_pk_bf16_f32 v106, v107, v108
	v_cvt_pk_bf16_f32 v108, v120, v121
	v_exp_f32_e32 v120, v80
	v_exp_f32_e32 v121, v64
	v_add_f32_e32 v99, v125, v99
	v_add_f32_e32 v97, v109, v97
	v_cvt_pk_bf16_f32 v107, v109, v110
	v_cvt_pk_bf16_f32 v109, v122, v123
	v_exp_f32_e32 v122, v81
	v_exp_f32_e32 v123, v65
	v_add_f32_e32 v99, v126, v99
	v_add_f32_e32 v97, v110, v97
	v_cvt_pk_bf16_f32 v110, v124, v125
	v_exp_f32_e32 v124, v82
	v_exp_f32_e32 v125, v66
	v_add_f32_e32 v99, v111, v99
	v_cvt_pk_bf16_f32 v111, v126, v111
	v_exp_f32_e32 v66, v83
	v_exp_f32_e32 v126, v67
	v_exp_f32_e32 v81, v84
	v_exp_f32_e32 v80, v68
	v_add_f32_e32 v64, v122, v120
	v_add_f32_e32 v65, v123, v121
	v_exp_f32_e32 v83, v85
	v_exp_f32_e32 v82, v69
	v_add_f32_e32 v64, v124, v64
	v_add_f32_e32 v67, v125, v65
	v_exp_f32_e32 v85, v86
	v_exp_f32_e32 v84, v70
	v_add_f32_e32 v97, v99, v97
	v_add_f32_e32 v65, v66, v64
	v_add_f32_e32 v64, v126, v67
	v_exp_f32_e32 v87, v87
	v_exp_f32_e32 v86, v71
	v_cmp_lt_f32_e32 vcc, s100, v97
	s_cbranch_vccnz .Lgq_redo0
	v_fmac_f32_e32 v222, s101, v97
	v_cvt_pk_bf16_f32 v96, v112, v96
	v_cvt_pk_bf16_f32 v97, v114, v98
	v_cvt_pk_bf16_f32 v98, v116, v100
	v_cvt_pk_bf16_f32 v100, v228, v113
	v_exp_f32_e32 v113, v88
	v_exp_f32_e32 v112, v72
	v_add_f32_e32 v64, v80, v64
	v_add_f32_e32 v65, v81, v65
	v_exp_f32_e32 v89, v89
	v_exp_f32_e32 v88, v73
	v_add_f32_e32 v64, v82, v64
	v_add_f32_e32 v65, v83, v65
	v_cvt_pk_bf16_f32 v99, v101, v102
	v_cvt_pk_bf16_f32 v101, v233, v115
	v_exp_f32_e32 v115, v90
	v_exp_f32_e32 v114, v74
	v_add_f32_e32 v64, v84, v64
	v_add_f32_e32 v65, v85, v65
	v_exp_f32_e32 v91, v91
	v_exp_f32_e32 v90, v75
	v_add_f32_e32 v64, v86, v64
	v_add_f32_e32 v65, v87, v65
	v_cvt_pk_bf16_f32 v102, v229, v117
	v_exp_f32_e32 v117, v92
	v_exp_f32_e32 v116, v76
	v_add_f32_e32 v64, v112, v64
	v_add_f32_e32 v65, v113, v65
	v_exp_f32_e32 v93, v93
	v_exp_f32_e32 v92, v77
	v_add_f32_e32 v64, v88, v64
	v_add_f32_e32 v65, v89, v65
	v_cvt_pk_bf16_f32 v103, v118, v103
	v_cvt_pk_bf16_f32 v104, v119, v104
	v_exp_f32_e32 v119, v94
	v_exp_f32_e32 v118, v78
	v_add_f32_e32 v64, v114, v64
	v_add_f32_e32 v65, v115, v65
	v_exp_f32_e32 v95, v95
	v_exp_f32_e32 v94, v79
	v_add_f32_e32 v64, v90, v64
	v_add_f32_e32 v65, v91, v65
	v_cvt_pk_bf16_f32 v67, v85, v87
	v_add_f32_e32 v64, v116, v64
	v_add_f32_e32 v65, v117, v65
	v_cvt_pk_bf16_f32 v68, v121, v123
	v_add_f32_e32 v64, v92, v64
	v_add_f32_e32 v65, v93, v65
	v_cvt_pk_bf16_f32 v69, v125, v126
	v_add_f32_e32 v64, v118, v64
	v_add_f32_e32 v65, v119, v65
	v_cvt_pk_bf16_f32 v70, v80, v82
	v_add_f32_e32 v64, v94, v64
	v_add_f32_e32 v65, v95, v65
	v_cvt_pk_bf16_f32 v71, v84, v86
	v_add_f32_e32 v64, v64, v65
	v_cmp_lt_f32_e32 vcc, s100, v64
	s_cbranch_vccnz .Lgq_redo1
	v_add_f32_e32 v227, v227, v64
	v_cvt_pk_bf16_f32 v64, v120, v122
	v_cvt_pk_bf16_f32 v65, v124, v66
	v_cvt_pk_bf16_f32 v66, v81, v83
	v_cvt_pk_bf16_f32 v72, v113, v89
	v_cvt_pk_bf16_f32 v73, v115, v91
	v_cvt_pk_bf16_f32 v74, v117, v93
	v_cvt_pk_bf16_f32 v75, v119, v95
	v_cvt_pk_bf16_f32 v76, v112, v88
	v_cvt_pk_bf16_f32 v77, v114, v90
	v_cvt_pk_bf16_f32 v78, v116, v92
	v_cvt_pk_bf16_f32 v79, v118, v94
	s_waitcnt lgkmcnt(0)
	v_mfma_f32_32x32x16_bf16 v[48:63], v[188:191], v[96:99], v[48:63]
	s_waitcnt vmcnt(0)
	s_add_i32 s2, s13, s10
	s_addk_i32 s45, 0x4000
	s_cmpk_lg_i32 s2, 0x83
	s_waitcnt vmcnt(0)
	s_barrier
	v_mfma_f32_32x32x16_bf16 v[32:47], v[184:187], v[96:99], v[32:47]
	v_mfma_f32_32x32x16_bf16 v[16:31], v[188:191], v[64:67], v[16:31]
	v_mfma_f32_32x32x16_bf16 v[0:15], v[184:187], v[64:67], v[0:15]
	v_mfma_f32_32x32x16_bf16 v[48:63], v[180:183], v[104:107], v[48:63]
	v_mfma_f32_32x32x16_bf16 v[32:47], v[176:179], v[104:107], v[32:47]
	v_mfma_f32_32x32x16_bf16 v[16:31], v[180:183], v[72:75], v[16:31]
	v_mfma_f32_32x32x16_bf16 v[0:15], v[176:179], v[72:75], v[0:15]
	v_mfma_f32_32x32x16_bf16 v[48:63], v[172:175], v[100:103], v[48:63]
	v_mfma_f32_32x32x16_bf16 v[32:47], v[168:171], v[100:103], v[32:47]
	v_mfma_f32_32x32x16_bf16 v[16:31], v[172:175], v[68:71], v[16:31]
	v_mfma_f32_32x32x16_bf16 v[0:15], v[168:171], v[68:71], v[0:15]
	v_mfma_f32_32x32x16_bf16 v[48:63], v[164:167], v[108:111], v[48:63]
	v_mfma_f32_32x32x16_bf16 v[32:47], v[160:163], v[108:111], v[32:47]
	v_mfma_f32_32x32x16_bf16 v[16:31], v[164:167], v[76:79], v[16:31]
	v_mfma_f32_32x32x16_bf16 v[0:15], v[160:163], v[76:79], v[0:15]
	s_cbranch_scc0 .LBB0_147

.LBB0_141:
	s_cmp_eq_u32 s100, 0x7f800001
	s_cbranch_scc1 .Lgq_exact
	s_mov_b32 s101, 1.0
	s_add_i32 s10, s10, 1
	s_and_b32 s2, s10, 3
	s_mov_b32 s100, 0x7f800000
	s_cmp_eq_u32 s2, 0
	s_cmov_b32 s100, 0x53800000
	s_mov_b64 s[42:43], 0
	s_branch .LBB0_144
.Lgq_exact:
	s_mov_b32 s100, 0x7f800000
	s_mov_b64 s[42:43], -1
	s_nop 3
	v_max_f32_e32 v160, v111, v111
	v_max_f32_e32 v161, v127, v127
	v_max_f32_e32 v160, v161, v160
	v_max3_f32 v161, v160, v112, v113
	v_max3_f32 v160, v160, v96, v97
	s_nop 0
	v_max3_f32 v160, v160, v98, v99
	v_max3_f32 v161, v161, v114, v115
	s_nop 0
	v_max3_f32 v160, v160, v100, v101
	v_max3_f32 v161, v161, v116, v117
	s_nop 0
	v_max3_f32 v160, v160, v102, v103
	v_max3_f32 v161, v161, v118, v119
	s_nop 0
	v_max3_f32 v160, v160, v104, v105
	v_max3_f32 v161, v161, v120, v121
	s_nop 0
	v_max3_f32 v160, v160, v106, v107
	v_max3_f32 v161, v161, v122, v123
	s_nop 0
	v_max3_f32 v160, v160, v108, v109
	v_max3_f32 v161, v161, v124, v125
	s_nop 0
	v_max3_f32 v160, v161, v160, v126
	s_nop 0
	v_max3_f32 v160, v160, v110, v160
	s_nop 0
	v_cmp_lt_f32_e32 vcc, s7, v160
	s_cbranch_vccz .LBB0_144
	v_cmp_lt_i32_e32 vcc, v225, v224
	s_mov_b64 s[28:29], -1
	s_nop 0
	v_cndmask_b32_e32 v161, v223, v225, vcc
	v_lshlrev_b32_e32 v161, 2, v161
	ds_bpermute_b32 v161, v161, v160
	v_max_f32_e32 v160, v160, v160
	s_waitcnt lgkmcnt(0)
	v_max_f32_e32 v161, v161, v161
	v_max_f32_e32 v160, v160, v161
	v_cmp_lt_f32_e32 vcc, s7, v160
	s_nop 1
	v_cndmask_b32_e32 v161, 0, v160, vcc
	v_exp_f32_e64 v160, -v161
	v_add_f32_e32 v206, v206, v161
	v_sub_f32_e32 v127, v127, v161
	v_sub_f32_e32 v126, v126, v161
	v_pk_mul_f32 v[62:63], v[62:63], v[160:161] op_sel_hi:[1,0]
	v_pk_mul_f32 v[60:61], v[60:61], v[160:161] op_sel_hi:[1,0]
	v_pk_mul_f32 v[58:59], v[58:59], v[160:161] op_sel_hi:[1,0]
	v_pk_mul_f32 v[56:57], v[56:57], v[160:161] op_sel_hi:[1,0]
	v_pk_mul_f32 v[54:55], v[54:55], v[160:161] op_sel_hi:[1,0]
	v_pk_mul_f32 v[52:53], v[52:53], v[160:161] op_sel_hi:[1,0]
	v_pk_mul_f32 v[50:51], v[50:51], v[160:161] op_sel_hi:[1,0]
	v_pk_mul_f32 v[48:49], v[48:49], v[160:161] op_sel_hi:[1,0]
	v_pk_mul_f32 v[46:47], v[46:47], v[160:161] op_sel_hi:[1,0]
	v_pk_mul_f32 v[44:45], v[44:45], v[160:161] op_sel_hi:[1,0]
	v_pk_mul_f32 v[42:43], v[42:43], v[160:161] op_sel_hi:[1,0]
	v_pk_mul_f32 v[40:41], v[40:41], v[160:161] op_sel_hi:[1,0]
	v_pk_mul_f32 v[38:39], v[38:39], v[160:161] op_sel_hi:[1,0]
	v_pk_mul_f32 v[36:37], v[36:37], v[160:161] op_sel_hi:[1,0]
	v_pk_mul_f32 v[34:35], v[34:35], v[160:161] op_sel_hi:[1,0]
	v_pk_mul_f32 v[32:33], v[32:33], v[160:161] op_sel_hi:[1,0]
	v_mul_f32_e32 v222, v222, v160
	v_sub_f32_e32 v125, v125, v161
	v_sub_f32_e32 v124, v124, v161
	v_sub_f32_e32 v123, v123, v161
	v_sub_f32_e32 v122, v122, v161
	v_sub_f32_e32 v121, v121, v161
	v_sub_f32_e32 v120, v120, v161
	v_sub_f32_e32 v119, v119, v161
	v_sub_f32_e32 v118, v118, v161
	v_sub_f32_e32 v117, v117, v161
	v_sub_f32_e32 v116, v116, v161
	v_sub_f32_e32 v115, v115, v161
	v_sub_f32_e32 v114, v114, v161
	v_sub_f32_e32 v113, v113, v161
	v_sub_f32_e32 v112, v112, v161
	v_sub_f32_e32 v111, v111, v161
	v_sub_f32_e32 v110, v110, v161
	v_sub_f32_e32 v109, v109, v161
	v_sub_f32_e32 v108, v108, v161
	v_sub_f32_e32 v107, v107, v161
	v_sub_f32_e32 v106, v106, v161
	v_sub_f32_e32 v105, v105, v161
	v_sub_f32_e32 v104, v104, v161
	v_sub_f32_e32 v103, v103, v161
	v_sub_f32_e32 v102, v102, v161
	v_sub_f32_e32 v101, v101, v161
	v_sub_f32_e32 v100, v100, v161
	v_sub_f32_e32 v99, v99, v161
	v_sub_f32_e32 v98, v98, v161
	v_sub_f32_e32 v97, v97, v161
	v_sub_f32_e32 v96, v96, v161

.Lgq_redo1:
	s_mov_b32 s101, 0
.Lgq_redo0:
	s_mov_b32 s100, 0x7f800001
	s_waitcnt lgkmcnt(0)
	v_add_u32_e32 v162, s46, v244
	v_add_u32_e32 v161, s46, v245
	v_add_u32_e32 v160, s46, v246
	v_add_u32_e32 v163, s46, v243
	ds_read_b128 v[164:167], v162
	ds_read_b128 v[168:171], v162 offset:4096
	ds_read_b128 v[172:175], v161
	ds_read_b128 v[176:179], v161 offset:4096
	ds_read_b128 v[180:183], v160
	ds_read_b128 v[184:187], v160 offset:4096
	s_branch .LBB0_137
